# select fast path: the next query's score rows are requested as soon as the current query's values are dead (flag in v248), mask-word address moved off v[2:3]
# speedup vs baseline: 1.0129x; 1.0072x over previous
.LBB0_697:
	v_mov_b32_e32 v248, 0
	v_readlane_b32 s4, v251, 0
	v_readlane_b32 s24, v251, 44
	v_writelane_b32 v252, s89, 12
	s_bitcmp1_b32 s4, 3
	s_mul_i32 s2, s88, 0x1c00
	v_mul_u32_u24_e32 v151, 12, v198
	v_readlane_b32 s25, v251, 45
	v_readlane_b32 s26, v251, 46
	v_readlane_b32 s27, v251, 47
	v_readlane_b32 s28, v251, 48
	v_readlane_b32 s29, v251, 49
	v_readlane_b32 s31, v251, 51
	v_readlane_b32 s30, v251, 50
	s_cbranch_scc1 .LBB0_1067
	v_cmp_eq_u32_e64 s[0:1], 0, v0
	v_lshlrev_b32_e32 v1, 6, v0
	v_and_b32_e32 v74, 0x3c0, v1
	v_writelane_b32 v252, s0, 13
	v_mov_b32_e32 v75, 0
	v_lshl_add_u64 v[2:3], s[26:27], 0, v[74:75]
	v_writelane_b32 v252, s1, 14
	s_lshl_b32 s0, s31, 6
	s_add_i32 s0, s0, 0
	s_ashr_i32 s1, s0, 31
	s_lshl_b64 s[0:1], s[0:1], 2
	s_add_u32 s0, s26, s0
	s_addc_u32 s1, s27, s1
	s_add_u32 s0, s0, 0x10000
	s_addc_u32 s1, s1, 0
	v_writelane_b32 v252, s0, 15
	v_lshrrev_b32_e32 v152, 4, v0
	v_and_b32_e32 v150, 31, v0
	v_writelane_b32 v252, s1, 16
	s_lshl_b32 s0, s88, 8
	s_add_i32 s6, s0, 0
	s_mov_b64 s[0:1], 0xb100000
	v_lshl_add_u64 v[76:77], v[2:3], 0, s[0:1]
	s_movk_i32 s0, 0x410
	v_mad_u32_u24 v6, v152, s0, 0
	s_add_u32 s0, s26, 0xbc00000
	s_addc_u32 s1, s27, 0
	v_writelane_b32 v252, s0, 17
	v_lshrrev_b32_e32 v2, 1, v198
	v_and_b32_e32 v2, 16, v2
	v_writelane_b32 v252, s1, 18
	s_mul_i32 s0, s88, 0x300
	s_add_i32 s33, s6, s0
	s_add_u32 s0, s26, 0x14d00000
	s_addc_u32 s1, s27, 0
	s_add_i32 s54, s33, s2
	v_mov_b32_e32 v3, v75
	v_writelane_b32 v252, s2, 19
	v_lshl_add_u64 v[4:5], s[26:27], 0, v[2:3]
	s_mov_b64 s[2:3], 0xba00000
	s_bitcmp0_b32 s4, 5
	v_lshl_add_u64 v[78:79], v[4:5], 0, s[2:3]
	s_cselect_b64 s[2:3], -1, 0
	v_writelane_b32 v252, s2, 21
	v_mul_u32_u24_e32 v4, 0x410, v150
	v_add3_u32 v154, 0, v4, v2
	v_writelane_b32 v252, s3, 22
	s_add_u32 s2, s26, 0x14a00000
	v_writelane_b32 v252, s2, 23
	s_addc_u32 s2, s27, 0
	s_bitcmp0_b32 s4, 6
	v_readlane_b32 s4, v251, 1
	v_lshl_add_u64 v[80:81], s[0:1], 0, v[2:3]
	v_writelane_b32 v252, s2, 25
	s_cselect_b64 s[2:3], -1, 0
	s_cmpk_lt_u32 s4, 0x800
	v_lshlrev_b32_e32 v2, 4, v198
	s_cselect_b64 s[4:5], -1, 0
	v_lshl_add_u64 v[84:85], s[0:1], 0, v[2:3]
	s_movk_i32 s0, 0x7e0
	s_and_b64 s[2:3], s[2:3], s[4:5]
	v_bitop3_b32 v159, v1, s0, v198 bitop3:0xc8
	s_lshl_b32 s0, s88, 13
	v_writelane_b32 v252, s2, 27
	v_lshlrev_b32_e32 v2, 7, v0
	v_lshrrev_b32_e32 v3, 2, v198
	s_add_i32 s0, s0, 0
	v_writelane_b32 v252, s3, 28
	v_lshlrev_b32_e32 v82, 2, v198
	v_and_b32_e32 v2, 0x80, v2
	v_and_b32_e32 v3, 12, v3
	s_add_i32 s86, s0, 0xc800
	s_add_i32 s0, 0, 0x25040
	v_add_u32_e32 v155, s33, v82
	v_add3_u32 v157, s6, v2, v3
	v_lshlrev_b32_e32 v2, 1, v0
	v_writelane_b32 v252, s0, 29
	s_waitcnt lgkmcnt(0)
	s_mov_b32 s47, 0
	v_lshl_or_b32 v153, s88, 5, v150
	v_or_b32_e32 v86, 1, v82
	v_or_b32_e32 v88, 2, v82
	v_or_b32_e32 v90, 3, v82
	s_movk_i32 s55, 0x100
	v_or_b32_e32 v92, 0x100, v82
	v_or_b32_e32 v94, 0x101, v82
	v_or_b32_e32 v96, 0x102, v82
	v_or_b32_e32 v98, 0x103, v82
	v_or_b32_e32 v100, 0x200, v82
	v_or_b32_e32 v102, 0x201, v82
	v_or_b32_e32 v104, 0x202, v82
	v_or_b32_e32 v106, 0x203, v82
	v_or_b32_e32 v108, 0x300, v82
	v_or_b32_e32 v110, 0x301, v82
	v_or_b32_e32 v112, 0x302, v82
	v_or_b32_e32 v114, 0x303, v82
	v_or_b32_e32 v116, 0x400, v82
	v_or_b32_e32 v118, 0x401, v82
	v_or_b32_e32 v120, 0x402, v82
	v_or_b32_e32 v122, 0x403, v82
	v_or_b32_e32 v124, 0x500, v82
	v_or_b32_e32 v126, 0x501, v82
	v_or_b32_e32 v128, 0x502, v82
	v_or_b32_e32 v130, 0x503, v82
	v_or_b32_e32 v132, 0x600, v82
	v_or_b32_e32 v134, 0x601, v82
	v_or_b32_e32 v136, 0x602, v82
	v_or_b32_e32 v138, 0x603, v82
	v_or_b32_e32 v140, 0x700, v82
	v_or_b32_e32 v142, 0x701, v82
	v_or_b32_e32 v144, 0x702, v82
	v_or_b32_e32 v146, 0x703, v82
	v_add_u32_e32 v156, s6, v82
	v_and_b32_e32 v158, 28, v2
	s_movk_i32 s87, 0xff
	v_add_u32_e32 v160, v6, v74
	v_mov_b32_e32 v161, 1
	v_mov_b32_e32 v162, 0xff800000
	v_mov_b32_e32 v163, 0x7f800000
	v_add_u32_e32 v164, v155, v151
	v_writelane_b32 v252, s54, 31
	s_branch .LBB0_702

.LBB0_721:
	s_add_i32 s4, s28, s89
	s_cmpk_gt_i32 s4, 0xff
	s_cbranch_scc0 .Lsel_orig
	s_lshr_b32 s6, s4, 8
	s_and_b32 s7, s4, 0xff
	s_and_b32 s80, s28, 7
	s_add_i32 s0, s28, s13
	s_ashr_i32 s1, s0, 31
	s_lshl_b64 s[0:1], s[0:1], 13
	s_mov_b64 s[2:3], 0x1000
	s_nop 0
	v_lshl_add_u64 v[34:35], v[84:85], 0, s[0:1]
	v_lshl_add_u64 v[184:185], v[34:35], 0, s[2:3]
	v_readfirstlane_b32 s5, v248
	v_mov_b32_e32 v248, 0
	s_cmp_eq_u32 s5, 1
	s_cbranch_scc1 .Lsel_ld_done
	global_load_dwordx4 v[2:5], v[34:35], off
	global_load_dwordx4 v[6:9], v[34:35], off offset:1024
	s_cmpk_lt_u32 s6, 2
	s_cbranch_scc1 .Lsel_ld_done
	global_load_dwordx4 v[10:13], v[34:35], off offset:2048
	s_cmpk_lt_u32 s6, 3
	s_cbranch_scc1 .Lsel_ld_done
	global_load_dwordx4 v[14:17], v[34:35], off offset:3072
	s_cmpk_lt_u32 s6, 4
	s_cbranch_scc1 .Lsel_ld_done
	global_load_dwordx4 v[18:21], v[184:185], off
	s_cmpk_lt_u32 s6, 5
	s_cbranch_scc1 .Lsel_ld_done
	global_load_dwordx4 v[22:25], v[184:185], off offset:1024
	s_cmpk_lt_u32 s6, 6
	s_cbranch_scc1 .Lsel_ld_done
	global_load_dwordx4 v[26:29], v[184:185], off offset:2048
	s_cmpk_lt_u32 s6, 7
	s_cbranch_scc1 .Lsel_ld_done
	global_load_dwordx4 v[30:33], v[184:185], off offset:3072

.Lsel_E:
	v_mov_b32_e32 v248, 0
	s_cmp_lt_u32 s28, 24
	s_cbranch_scc0 .Lsel_nopf
	s_add_i32 s0, s28, s89
	s_add_i32 s0, s0, 8
	s_lshr_b32 s0, s0, 8
	s_mov_b64 s[2:3], 0x10000
	s_nop 1
	v_lshl_add_u64 v[34:35], v[34:35], 0, s[2:3]
	v_lshl_add_u64 v[184:185], v[184:185], 0, s[2:3]
	global_load_dwordx4 v[2:5], v[34:35], off
	global_load_dwordx4 v[6:9], v[34:35], off offset:1024
	s_cmpk_lt_u32 s0, 2
	s_cbranch_scc1 .Lsel_pf_done
	global_load_dwordx4 v[10:13], v[34:35], off offset:2048
	s_cmpk_lt_u32 s0, 3
	s_cbranch_scc1 .Lsel_pf_done
	global_load_dwordx4 v[14:17], v[34:35], off offset:3072
	s_cmpk_lt_u32 s0, 4
	s_cbranch_scc1 .Lsel_pf_done
	global_load_dwordx4 v[18:21], v[184:185], off
	s_cmpk_lt_u32 s0, 5
	s_cbranch_scc1 .Lsel_pf_done
	global_load_dwordx4 v[22:25], v[184:185], off offset:1024
	s_cmpk_lt_u32 s0, 6
	s_cbranch_scc1 .Lsel_pf_done
	global_load_dwordx4 v[26:29], v[184:185], off offset:2048
	s_cmpk_lt_u32 s0, 7
	s_cbranch_scc1 .Lsel_pf_done
	global_load_dwordx4 v[30:33], v[184:185], off offset:3072
.Lsel_pf_done:
	v_mov_b32_e32 v248, 1

.Lsel_E_0:
	v_sub_u32_e32 v193, v196, v202
	v_sub_u32_e32 v192, v196, v201
	v_sub_u32_e32 v187, v196, v200
	v_sub_u32_e32 v186, v196, v199
	v_alignbit_b32 v195, v195, v193, 31
	v_alignbit_b32 v195, v195, v192, 31
	v_alignbit_b32 v195, v195, v187, 31
	v_alignbit_b32 v195, v195, v186, 31
	s_and_b32 s7, s28, 7
	s_lshl_b32 s7, s7, 8
	s_add_i32 s7, s7, 0xc000
	v_and_b32_e32 v186, 1, v198
	v_lshlrev_b32_e32 v186, 7, v186
	v_lshrrev_b32_e32 v187, 4, v198
	v_lshl_add_u32 v186, v187, 2, v186
	v_add_u32_e32 v186, s7, v186
	v_lshlrev_b32_e32 v187, 1, v198
	v_and_b32_e32 v187, 28, v187
	v_bfe_u32 v192, v195, 0, 4
	v_lshlrev_b32_e32 v192, v187, v192
	ds_or_b32 v186, v192
	v_bfe_u32 v193, v195, 4, 4
	v_lshlrev_b32_e32 v193, v187, v193
	ds_or_b32 v186, v193 offset:16
	v_bfe_u32 v240, v195, 8, 4
	v_lshlrev_b32_e32 v240, v187, v240
	ds_or_b32 v186, v240 offset:32
	v_bfe_u32 v241, v195, 12, 4
	v_lshlrev_b32_e32 v241, v187, v241
	ds_or_b32 v186, v241 offset:48
	v_bfe_u32 v192, v195, 16, 4
	v_lshlrev_b32_e32 v192, v187, v192
	ds_or_b32 v186, v192 offset:64
	v_bfe_u32 v193, v195, 20, 4
	v_lshlrev_b32_e32 v193, v187, v193
	ds_or_b32 v186, v193 offset:80
	v_bfe_u32 v240, v195, 24, 4
	v_lshlrev_b32_e32 v240, v187, v240
	ds_or_b32 v186, v240 offset:96
	v_bfe_u32 v241, v195, 28, 4
	v_lshlrev_b32_e32 v241, v187, v241
	ds_or_b32 v186, v241 offset:112
	s_waitcnt lgkmcnt(0)
	ds_read_b32 v1, v237
	v_add_u32_e32 v74, s28, v159
	v_lshl_add_u64 v[186:187], v[74:75], 2, s[20:21]
	s_waitcnt lgkmcnt(0)
	global_store_dword v[186:187], v1, off
	s_add_i32 s0, s28, 8
	s_cmp_lt_u32 s28, 24
	s_mov_b32 s28, s0
	s_cbranch_scc0 .LBB0_699
	s_branch .LBB0_721
